# v91 + GDN scan step's first half no longer waits for the previous step's output stores (operand loads are known complete at the latch; one wait in front of the loop for the first step)
# baseline (speedup 1.0000x reference)
; #define LAS __attribute__((address_space(3)))
; __device__ __forceinline__ void lds_barrier() { asm volatile("s_waitcnt lgkmcnt(0)" ::: "memory"); __builtin_amdgcn_s_barrier(); asm volatile("" ::: "memory"); }
; __device__ __forceinline__ void chain_load(ChainOps& o, const GdnP& P, int b, int h, int n, int w, int mt, int nh, int lane, int tid) {
;     const int l15 = lane & 15, quad = lane >> 4;
;     const int cn = b * 64 + n, unit = cn * 8 + h, row0 = cn * 64;
;     const bf16_t* wrow = P.wbuf + (size_t)unit * 8192 + (mt * 16 + l15) * 128 + quad * 8;
;     const bf16_t* qrow = P.proj + (size_t)(row0 + mt * 16 + l15) * NIN + C_GDN + h * 128 + quad * 8;
; #pragma unroll
;     for (int s = 0; s < 4; ++s) { o.wf[s] = *(const bf16x8*)(wrow + 32 * s); o.qf[s] = *(const bf16x8*)(qrow + 32 * s); }
;     const bf16_t* arow = P.attnb + (size_t)unit * 4096 + (mt * 16 + l15) * 64 + quad * 8;
;     const int kidx = w * 16 + l15;
;     const bf16_t* krow = P.proj + (size_t)(row0 + (kidx >> 1)) * NIN + C_GDN + 1024 + h * 128 + (kidx & 1) * 64 + quad * 8;
; #pragma unroll
;     for (int s = 0; s < 2; ++s) { o.af[s] = *(const bf16x8*)(arow + 32 * s); o.kf[s] = *(const bf16x8*)(krow + 32 * s); }
;     o.cd = P.cdb[unit];
;     const int cb = ((mt * 2 + nh) * 64 + lane) * 2;
;     const bf16_t* up = P.proj + (size_t)(row0 + (cb >> 4)) * NIN + C_GDN + 2048 + h * 128 + (cb & 15) * 8;
;     o.uf[0] = *(const u32x4*)up; o.uf[1] = *(const u32x4*)(up + 8);
; }
; __device__ __forceinline__ void gdn_chain(LAS unsigned char* lds, const GdnP& P, const float* out_norm, int bh, const int tid) {
;     const int w = __builtin_amdgcn_readfirstlane(tid >> 6), lane = tid & 63, l15 = lane & 15, quad = lane >> 4;
;     const int b = bh >> 3, h = bh & 7, mt = w & 3, nh = w >> 2;
;     f32x4 sacc[8];
; #pragma unroll
;     for (int n = 0; n < 8; ++n) sacc[n] = (f32x4){0.f, 0.f, 0.f, 0.f};
;     lds_barrier();
;     for (int i = tid; i < 34816 / 16; i += 512) *(LAS u32x4*)(lds + GC_ST + i * 16) = (u32x4){0u, 0u, 0u, 0u};
;     ChainOps cur, nxt;
;     chain_load(cur, P, b, h, 0, w, mt, nh, lane, tid);
;     lds_barrier();
.Lgf_onorm_skip:
	s_or_b64 exec, exec, s[70:71]
	s_ashr_i32 s29, s42, 3
	s_ashr_i32 s46, s0, 6
	s_and_b32 s43, s42, 7
	s_ashr_i32 s48, s0, 8
	s_mov_b32 s59, s48
	s_lshl_b32 s0, s29, 9
	s_or_b32 s28, s0, s43
	s_lshl_b32 s44, s29, 6
	s_lshl_b32 s49, s29, 12
	s_ashr_i32 s29, s28, 31
	s_and_b32 s47, s46, 3
	s_lshl_b64 s[30:31], s[28:29], 14
	s_add_u32 s30, s18, s30
	s_addc_u32 s31, s19, s31
	s_lshl_b32 s50, s47, 4
	v_or_b32_e32 v152, s50, v113
	v_lshlrev_b32_e32 v26, 8, v152
	v_mov_b32_e32 v27, v115
	v_lshl_add_u64 v[0:1], s[30:31], 0, v[26:27]
	v_lshl_add_u64 v[8:9], v[0:1], 0, v[114:115]
	v_or_b32_e32 v0, s49, v152
	v_mad_i64_i32 v[0:1], s[30:31], v0, s40, v[120:121]
	s_lshl_b32 s45, s43, 7
	s_lshl_b32 s0, s43, 8
	s_lshl_b64 s[30:31], s[28:29], 13
	v_lshl_or_b32 v34, s46, 4, v113
	s_add_u32 s30, s20, s30
	v_ashrrev_i32_e32 v153, 1, v34
	v_lshlrev_b32_e32 v24, 7, v152
	v_mov_b32_e32 v25, v115
	s_addc_u32 s31, s21, s31
	v_add_u32_e32 v34, s49, v153
	v_lshl_add_u64 v[0:1], v[0:1], 0, s[0:1]
	v_lshl_add_u64 v[32:33], s[30:31], 0, v[24:25]
	v_mad_i64_i32 v[34:35], s[30:31], v34, s40, v[120:121]
	v_lshl_add_u64 v[0:1], v[0:1], 0, v[114:115]
	v_lshl_add_u64 v[34:35], v[34:35], 0, s[0:1]
	v_add_co_u32_e32 v28, vcc, s41, v0
	v_lshl_add_u64 v[34:35], v[34:35], 0, v[124:125]
	s_lshl_b64 s[28:29], s[28:29], 2
	v_addc_co_u32_e32 v29, vcc, 0, v1, vcc
	v_lshl_add_u64 v[34:35], v[34:35], 0, v[114:115]
	s_add_u32 s28, s2, s28
	v_lshl_add_u64 v[10:11], v[0:1], 0, s[22:23]
	v_lshl_add_u64 v[32:33], v[32:33], 0, v[114:115]
	v_lshl_add_u64 v[36:37], v[34:35], 0, s[24:25]
	v_add_co_u32_e32 v34, vcc, s38, v34
	s_addc_u32 s29, s3, s29
	global_load_dwordx4 v[72:75], v[8:9], off
	global_load_dwordx4 v[12:15], v[8:9], off offset:64
	global_load_dwordx4 v[4:7], v[10:11], off offset:64
	global_load_dwordx4 v[0:3], v[10:11], off offset:128
	global_load_dwordx4 v[20:23], v[8:9], off offset:128
	global_load_dwordx4 v[16:19], v[8:9], off offset:192
	s_nop 0
	global_load_dwordx4 v[28:31], v[28:29], off offset:2048
	s_nop 0
	global_load_dwordx4 v[8:11], v[10:11], off offset:192
	v_addc_co_u32_e32 v35, vcc, 0, v35, vcc
	global_load_dwordx4 v[68:71], v[32:33], off
	global_load_dwordx4 v[44:47], v[32:33], off offset:64
	global_load_dwordx4 v[48:51], v[34:35], off
	s_nop 0
	global_load_dwordx4 v[36:39], v[36:37], off offset:64
	s_lshl_b32 s30, s48, 6
	global_load_dword v123, v115, s[28:29]
	s_lshl_b32 s28, s47, 7
	s_add_i32 s28, s28, s30
	v_or_b32_e32 v32, s28, v139
	v_ashrrev_i32_e32 v154, 3, v32
	v_add_u32_e32 v32, s49, v154
	v_mad_i64_i32 v[32:33], s[28:29], v32, s40, v[120:121]
	v_lshl_add_u64 v[32:33], v[32:33], 0, s[0:1]
	v_lshl_add_u64 v[32:33], v[32:33], 0, v[128:129]
	v_lshl_add_u64 v[34:35], v[32:33], 0, s[26:27]
	v_add_co_u32_e32 v32, vcc, s38, v32
	s_lshl_b32 s0, s48, 2
	s_nop 0
	v_addc_co_u32_e32 v33, vcc, 0, v33, vcc
	global_load_dwordx4 v[80:83], v[32:33], off offset:2048
	global_load_dwordx4 v[84:87], v[34:35], off offset:16
	v_or_b32_e32 v34, s30, v113
	s_or_b32 s28, s0, 1
	v_mul_lo_u32 v35, v34, s36
	v_mul_lo_u32 v156, v34, s37
	v_lshl_or_b32 v34, s28, 4, v113
	s_or_b32 s29, s0, 2
	v_or_b32_e32 v32, s50, v142
	v_lshl_add_u32 v33, s46, 5, v141
	s_add_i32 s46, s0, 0
	v_mul_lo_u32 v40, v34, s36
	v_mul_lo_u32 v157, v34, s37
	v_lshl_or_b32 v34, s29, 4, v113
	s_or_b32 s0, s0, 3
	s_waitcnt lgkmcnt(0)
	s_barrier
	v_mul_lo_u32 v41, v34, s36
	v_mul_lo_u32 v158, v34, s37
	v_lshl_or_b32 v34, s0, 4, v113
	v_lshl_add_u32 v54, s0, 5, v143
	v_lshlrev_b32_e32 v160, 3, v32
	s_lshl_b32 s0, s43, 2
	v_mul_lo_u32 v42, v34, s36
	v_mul_lo_u32 v159, v34, s37
	v_lshl_add_u32 v34, s48, 7, v143
	v_mul_u32_u24_e32 v43, 0x110, v32
	v_lshl_add_u32 v52, s28, 5, v143
	v_lshl_add_u32 v53, s29, 5, v143
	v_or_b32_e32 v32, 8, v160
	v_or_b32_e32 v55, 16, v160
	v_or_b32_e32 v56, 24, v160
	v_lshl_add_u64 v[134:135], v[118:119], 0, v[24:25]
	s_add_u32 s28, s33, s0
	v_mov_b32_e32 v24, 0
	v_lshl_add_u32 v155, s47, 5, v141
	v_lshl_add_u64 v[132:133], v[116:117], 0, v[26:27]
	s_addc_u32 s29, s35, 0
	v_add_u32_e32 v136, s49, v144
	s_movk_i32 s47, 0xffc0
	v_add_u32_e32 v161, v140, v35
	v_add_u32_e32 v162, v140, v40
	v_add_u32_e32 v163, v140, v41
	v_add_u32_e32 v164, v140, v42
	v_add_u32_e32 v165, v34, v43
	v_add_u32_e32 v166, v52, v43
	v_add_u32_e32 v167, v53, v43
	v_add_u32_e32 v168, v54, v43
	v_add_u32_e32 v169, v33, v145
	v_add_u32_e32 v170, s46, v32
	v_add_u32_e32 v171, s46, v55
	v_add_u32_e32 v172, s46, v56
	v_mov_b32_e32 v25, v24
	v_mov_b32_e32 v26, v24
	v_mov_b32_e32 v27, v24
	v_mov_b32_e32 v32, v24
	v_mov_b32_e32 v33, v24
	v_mov_b32_e32 v34, v24
	v_mov_b32_e32 v35, v24
	v_mov_b32_e32 v40, v24
	v_mov_b32_e32 v41, v24
	v_mov_b32_e32 v42, v24
	v_mov_b32_e32 v43, v24
	v_mov_b32_e32 v52, v24
	v_mov_b32_e32 v53, v24
	v_mov_b32_e32 v54, v24
	v_mov_b32_e32 v55, v24
	v_mov_b32_e32 v56, v24
	v_mov_b32_e32 v57, v24
	v_mov_b32_e32 v58, v24
	v_mov_b32_e32 v59, v24
	v_mov_b32_e32 v60, v24
	v_mov_b32_e32 v61, v24
	v_mov_b32_e32 v62, v24
	v_mov_b32_e32 v63, v24
	v_mov_b32_e32 v64, v24
	v_mov_b32_e32 v65, v24
	v_mov_b32_e32 v66, v24
	v_mov_b32_e32 v67, v24
	v_mov_b32_e32 v76, v24
	v_mov_b32_e32 v77, v24
	v_mov_b32_e32 v78, v24
	v_mov_b32_e32 v79, v24
	v_mov_b32_e32 v222, v130
	v_mov_b32_e32 v223, 0
	s_lshl_b32 s74, s45, 1
	s_mov_b32 s75, 0
	s_mov_b32 s78, 0x168000
	s_mov_b32 s79, 0
	v_mov_b64_e32 v[220:221], s[16:17]
	v_mad_i64_i32 v[220:221], s[56:57], v136, s40, v[220:221]
	v_lshl_add_u64 v[220:221], v[220:221], 0, s[74:75]
	v_lshl_add_u64 v[220:221], v[220:221], 0, v[222:223]
	v_lshl_add_u64 v[220:221], v[220:221], 0, s[26:27]
	global_load_dwordx4 v[244:247], v[220:221], off offset:2048
	global_load_dwordx4 v[248:251], v[220:221], off offset:2064
	s_waitcnt vmcnt(2)
	s_branch .LBB0_1126

; __device__ __forceinline__ void chain_load(ChainOps& o, const GdnP& P, int b, int h, int n, int w, int mt, int nh, int lane, int tid) {
;     const int l15 = lane & 15, quad = lane >> 4;
;     const int cn = b * 64 + n, unit = cn * 8 + h, row0 = cn * 64;
;     const bf16_t* wrow = P.wbuf + (size_t)unit * 8192 + (mt * 16 + l15) * 128 + quad * 8;
;     const bf16_t* qrow = P.proj + (size_t)(row0 + mt * 16 + l15) * NIN + C_GDN + h * 128 + quad * 8;
; #pragma unroll
;     for (int s = 0; s < 4; ++s) { o.wf[s] = *(const bf16x8*)(wrow + 32 * s); o.qf[s] = *(const bf16x8*)(qrow + 32 * s); }
;     const bf16_t* arow = P.attnb + (size_t)unit * 4096 + (mt * 16 + l15) * 64 + quad * 8;
;     const int kidx = w * 16 + l15;
;     const bf16_t* krow = P.proj + (size_t)(row0 + (kidx >> 1)) * NIN + C_GDN + 1024 + h * 128 + (kidx & 1) * 64 + quad * 8;
; #pragma unroll
;     for (int s = 0; s < 2; ++s) { o.af[s] = *(const bf16x8*)(arow + 32 * s); o.kf[s] = *(const bf16x8*)(krow + 32 * s); }
;     o.cd = P.cdb[unit];
;     const int cb = ((mt * 2 + nh) * 64 + lane) * 2;
;     const bf16_t* up = P.proj + (size_t)(row0 + (cb >> 4)) * NIN + C_GDN + 2048 + h * 128 + (cb & 15) * 8;
;     o.uf[0] = *(const u32x4*)up; o.uf[1] = *(const u32x4*)(up + 8);
; __device__ __forceinline__ void gdn_chain(LAS unsigned char* lds, const GdnP& P, const float* out_norm, int bh, const int tid) {
;     ...
;     for (int n = 0; n < 64; ++n) {
;         const int row0 = (b * 64 + n) * 64;
;         chain_load(nxt, P, b, h, n < 63 ? n + 1 : n, w, mt, nh, lane, tid);
;         f32x4 oacc[4];
; #pragma unroll
;         for (int q = 0; q < 4; ++q) { const int nt = 4 * nh + q; f32x4 a1 = (f32x4){0.f, 0.f, 0.f, 0.f}; oacc[q] = (f32x4){0.f, 0.f, 0.f, 0.f};
; #pragma unroll
;             for (int s = 0; s < 4; ++s) { const bf16x8 sf = *(const LAS bf16x8*)(lds + GC_ST + (nt * 16 + l15) * 272 + (quad * 8 + 32 * s) * 2);
;                 a1 = __builtin_amdgcn_mfma_f32_16x16x32_bf16(cur.wf[s], sf, a1, 0, 0, 0); oacc[q] = __builtin_amdgcn_mfma_f32_16x16x32_bf16(cur.qf[s], sf, oacc[q], 0, 0, 0); }
;             const unsigned u01 = cur.uf[q >> 1][(q & 1) * 2], u23 = cur.uf[q >> 1][(q & 1) * 2 + 1];
;             u32x2 pv; pv.x = pk2(bflo(u01) - a1[0], bfhi(u01) - a1[1]); pv.y = pk2(bflo(u23) - a1[2], bfhi(u23) - a1[3]);
;             *(LAS u32x2*)(lds + GC_VT + (nt * 16 + l15) * 144 + (mt * 16 + quad * 4) * 2) = pv; }
.LBB0_1126:
	s_waitcnt vmcnt(4)
	v_mov_b64_e32 v[90:91], v[74:75]
	v_mov_b64_e32 v[88:89], v[72:73]
	ds_read_b128 v[72:75], v161
	ds_read_b128 v[92:95], v161 offset:64
	s_waitcnt vmcnt(4)
	v_mov_b64_e32 v[106:107], v[14:15]
	v_mov_b64_e32 v[104:105], v[12:13]
	s_waitcnt vmcnt(4)
	v_mov_b64_e32 v[110:111], v[22:23]
	s_waitcnt lgkmcnt(1)
	v_mfma_f32_16x16x32_bf16 v[96:99], v[88:91], v[72:75], 0
	s_waitcnt vmcnt(4)
	v_mov_b64_e32 v[102:103], v[30:31]
	v_mov_b64_e32 v[108:109], v[20:21]
	ds_read_b128 v[20:23], v161 offset:128
	v_mov_b64_e32 v[100:101], v[28:29]
	s_waitcnt lgkmcnt(1)
	v_mfma_f32_16x16x32_bf16 v[28:31], v[104:107], v[92:95], v[96:99]
	v_mov_b64_e32 v[180:181], v[18:19]
	v_mov_b64_e32 v[184:185], v[6:7]
	v_mov_b64_e32 v[178:179], v[16:17]
	v_mov_b64_e32 v[182:183], v[4:5]
	ds_read_b128 v[4:7], v161 offset:192
	s_waitcnt lgkmcnt(1)
	v_mfma_f32_16x16x32_bf16 v[16:19], v[108:111], v[20:23], v[28:31]
	v_mov_b64_e32 v[188:189], v[2:3]
	v_mov_b64_e32 v[186:187], v[0:1]
	s_waitcnt vmcnt(4)
	v_mov_b64_e32 v[192:193], v[10:11]
	v_mfma_f32_16x16x32_bf16 v[12:15], v[100:103], v[72:75], 0
	v_mov_b64_e32 v[190:191], v[8:9]
	s_waitcnt vmcnt(4)
	v_lshlrev_b32_e32 v8, 16, v80
	v_and_b32_e32 v9, 0xffff0000, v80
	s_waitcnt lgkmcnt(0)
	v_mfma_f32_16x16x32_bf16 v[0:3], v[178:181], v[4:7], v[16:19]
	s_add_i32 s0, s47, 0x41
	s_cmp_lg_u32 s47, -1
	s_cselect_b32 s0, s0, 63
	s_add_i32 s0, s0, s44
	s_lshl_b32 s30, s0, 3
	s_nop 2
	v_pk_add_f32 v[0:1], v[8:9], v[0:1] neg_lo:[0,1] neg_hi:[0,1]
	v_mfma_f32_16x16x32_bf16 v[8:11], v[182:185], v[92:95], v[12:15]
	v_cvt_pk_bf16_f32 v0, v0, v1
	s_or_b32 s30, s30, s43
	s_lshl_b32 s50, s0, 6
	v_lshlrev_b32_e32 v12, 16, v81
	v_and_b32_e32 v13, 0xffff0000, v81
	v_pk_add_f32 v[2:3], v[12:13], v[2:3] neg_lo:[0,1] neg_hi:[0,1]
	v_mfma_f32_16x16x32_bf16 v[8:11], v[186:189], v[20:23], v[8:11]
	v_cvt_pk_bf16_f32 v1, v2, v3
	v_add_u32_e32 v2, v155, v156
	ds_write_b64 v2, v[0:1] offset:34816
	ds_read_b128 v[0:3], v162
	v_mfma_f32_16x16x32_bf16 v[198:201], v[190:193], v[4:7], v[8:11]
	ds_read_b128 v[4:7], v162 offset:64
	ds_read_b128 v[12:15], v162 offset:128
	s_ashr_i32 s31, s30, 31
	s_waitcnt lgkmcnt(2)
	v_mfma_f32_16x16x32_bf16 v[8:11], v[88:91], v[0:3], 0
	v_mov_b64_e32 v[94:95], v[38:39]
	s_lshl_b64 s[48:49], s[30:31], 14
	v_or_b32_e32 v18, s50, v152
	v_mfma_f32_16x16x32_bf16 v[0:3], v[100:103], v[0:3], 0
	v_mov_b64_e32 v[202:203], s[16:17]
	v_mov_b64_e32 v[92:93], v[36:37]
	v_lshl_add_u64 v[16:17], v[132:133], 0, s[48:49]
	s_waitcnt lgkmcnt(1)
	v_mfma_f32_16x16x32_bf16 v[8:11], v[104:107], v[4:7], v[8:11]
	s_lshl_b32 s0, s45, 1
	v_mov_b64_e32 v[196:197], v[70:71]
	v_mov_b64_e32 v[194:195], v[68:69]
	v_mfma_f32_16x16x32_bf16 v[0:3], v[182:185], v[4:7], v[0:3]
	ds_read_b128 v[4:7], v162 offset:192
	v_mov_b64_e32 v[208:209], v[46:47]
	v_mov_b64_e32 v[98:99], v[50:51]
	s_waitcnt lgkmcnt(1)
	v_mfma_f32_16x16x32_bf16 v[8:11], v[108:111], v[12:15], v[8:11]
	v_mov_b64_e32 v[206:207], v[44:45]
	v_mov_b64_e32 v[96:97], v[48:49]
	v_add_u32_e32 v80, s50, v153
	s_waitcnt lgkmcnt(0)
	v_mfma_f32_16x16x32_bf16 v[8:11], v[178:181], v[4:7], v[8:11]
	v_mov_b32_e32 v138, v123
	v_mov_b32_e32 v123, v115
	v_mov_b32_e32 v127, v115
	v_mfma_f32_16x16x32_bf16 v[0:3], v[186:189], v[12:15], v[0:3]
	v_lshlrev_b32_e32 v14, 16, v82
	v_and_b32_e32 v15, 0xffff0000, v82
	s_nop 1
	v_pk_add_f32 v[8:9], v[14:15], v[8:9] neg_lo:[0,1] neg_hi:[0,1]
	v_lshlrev_b32_e32 v14, 16, v83
	v_and_b32_e32 v15, 0xffff0000, v83
	v_pk_add_f32 v[10:11], v[14:15], v[10:11] neg_lo:[0,1] neg_hi:[0,1]
	v_cvt_pk_bf16_f32 v8, v8, v9
	v_cvt_pk_bf16_f32 v9, v10, v11
	v_add_u32_e32 v10, v155, v157
	ds_write_b64 v10, v[8:9] offset:34816
	ds_read_b128 v[8:11], v163
	ds_read_b128 v[36:39], v163 offset:64
	v_mad_i64_i32 v[12:13], s[48:49], v18, s40, v[202:203]
	v_lshl_add_u64 v[12:13], v[12:13], 0, s[0:1]
	s_waitcnt lgkmcnt(1)
	v_mfma_f32_16x16x32_bf16 v[28:31], v[88:91], v[8:11], 0
	s_lshl_b64 s[48:49], s[30:31], 13
	v_lshl_add_u64 v[218:219], v[134:135], 0, s[48:49]
	v_mad_i64_i32 v[80:81], s[48:49], v80, s40, v[202:203]
	v_mfma_f32_16x16x32_bf16 v[210:213], v[190:193], v[4:7], v[0:3]
	s_lshl_b64 s[30:31], s[30:31], 2
	s_add_u32 s30, s2, s30
	s_addc_u32 s31, s3, s31
	v_lshl_add_u64 v[0:1], v[12:13], 0, v[114:115]
	v_add_co_u32_e32 v70, vcc, s41, v0
	v_lshl_add_u64 v[68:69], v[0:1], 0, s[22:23]
	s_nop 0
	v_addc_co_u32_e32 v71, vcc, 0, v1, vcc
	global_load_dwordx4 v[72:75], v[16:17], off
	global_load_dwordx4 v[12:15], v[16:17], off offset:64
	v_mfma_f32_16x16x32_bf16 v[44:47], v[100:103], v[8:11], 0
	global_load_dwordx4 v[4:7], v[68:69], off offset:64
	global_load_dwordx4 v[0:3], v[68:69], off offset:128
	global_load_dwordx4 v[20:23], v[16:17], off offset:128
	s_nop 0
	global_load_dwordx4 v[16:19], v[16:17], off offset:192
	v_pk_mul_f32 v[66:67], v[66:67], v[138:139] op_sel_hi:[1,0]
	v_pk_mul_f32 v[64:65], v[64:65], v[138:139] op_sel_hi:[1,0]
	s_waitcnt lgkmcnt(0)
; __device__ __forceinline__ void chain_load(ChainOps& o, const GdnP& P, int b, int h, int n, int w, int mt, int nh, int lane, int tid) {
;     ...
;     for (int s = 0; s < 4; ++s) { o.wf[s] = *(const bf16x8*)(wrow + 32 * s); o.qf[s] = *(const bf16x8*)(qrow + 32 * s); }
; __device__ __forceinline__ void gdn_chain(LAS unsigned char* lds, const GdnP& P, const float* out_norm, int bh, const int tid) {
;     ...
;         for (int q = 0; q < 4; ++q) { const int nt = 4 * nh + q; f32x4 a1 = (f32x4){0.f, 0.f, 0.f, 0.f}; oacc[q] = (f32x4){0.f, 0.f, 0.f, 0.f};
; #pragma unroll
;             for (int s = 0; s < 4; ++s) { const bf16x8 sf = *(const LAS bf16x8*)(lds + GC_ST + (nt * 16 + l15) * 272 + (quad * 8 + 32 * s) * 2);
;                 a1 = __builtin_amdgcn_mfma_f32_16x16x32_bf16(cur.wf[s], sf, a1, 0, 0, 0); oacc[q] = __builtin_amdgcn_mfma_f32_16x16x32_bf16(cur.qf[s], sf, oacc[q], 0, 0, 0); }
;             const unsigned u01 = cur.uf[q >> 1][(q & 1) * 2], u23 = cur.uf[q >> 1][(q & 1) * 2 + 1];
;             u32x2 pv; pv.x = pk2(bflo(u01) - a1[0], bfhi(u01) - a1[1]); pv.y = pk2(bflo(u23) - a1[2], bfhi(u23) - a1[3]);
;             *(LAS u32x2*)(lds + GC_VT + (nt * 16 + l15) * 144 + (mt * 16 + quad * 4) * 2) = pv; }
;         lds_barrier();
;         float ss[4] = {0.f, 0.f, 0.f, 0.f};
; #pragma unroll
;         for (int q = 0; q < 4; ++q) { const int nt = 4 * nh + q;
; #pragma unroll
;             for (int s = 0; s < 2; ++s) { const bf16x8 vf = *(const LAS bf16x8*)(lds + GC_VT + (nt * 16 + l15) * 144 + (quad * 8 + 32 * s) * 2); oacc[q] = __builtin_amdgcn_mfma_f32_16x16x32_bf16(cur.af[s], vf, oacc[q], 0, 0, 0); }
; #pragma unroll
;             for (int i = 0; i < 4; ++i) { ss[i] += oacc[q][i] * oacc[q][i]; *(LAS bf16_t*)(lds + GC_OB + (mt * 16 + quad * 4 + i) * 272 + (nt * 16 + l15) * 2) = (bf16_t)f2bf(oacc[q][i]); } }
; #pragma unroll
;         for (int nt = 0; nt < 8; ++nt) { sacc[nt] = sacc[nt] * cur.cd;
; #pragma unroll
;             for (int s = 0; s < 2; ++s) { const bf16x8 vf = *(const LAS bf16x8*)(lds + GC_VT + (nt * 16 + l15) * 144 + (quad * 8 + 32 * s) * 2); sacc[nt] = __builtin_amdgcn_mfma_f32_16x16x32_bf16(cur.kf[s], vf, sacc[nt], 0, 0, 0); }
;             u32x2 pv; pv.x = pk2(sacc[nt][0], sacc[nt][1]); pv.y = pk2(sacc[nt][2], sacc[nt][3]);
;             *(LAS u32x2*)(lds + GC_ST + (nt * 16 + l15) * 272 + (w * 16 + quad * 4) * 2) = pv; }
	v_mfma_f32_16x16x32_bf16 v[48:51], v[104:107], v[36:39], v[28:31]
	s_nop 2
	global_load_dwordx4 v[28:31], v[70:71], off offset:2048
	global_load_dwordx4 v[8:11], v[68:69], off offset:192
	ds_read_b128 v[68:71], v163 offset:128
	v_pk_mul_f32 v[62:63], v[62:63], v[138:139] op_sel_hi:[1,0]
	v_mfma_f32_16x16x32_bf16 v[36:39], v[182:185], v[36:39], v[44:47]
	v_mul_f32_e64 v60, v60, v138
	v_mul_f32_e64 v61, v61, v138
	v_pk_mul_f32 v[58:59], v[58:59], v[138:139] op_sel_hi:[1,0]
	v_pk_mul_f32 v[56:57], v[56:57], v[138:139] op_sel_hi:[1,0]
	ds_read_b128 v[44:47], v163 offset:192
	s_waitcnt lgkmcnt(1)
	v_mfma_f32_16x16x32_bf16 v[48:51], v[108:111], v[68:71], v[48:51]
	v_mul_f32_e64 v54, v54, v138
	v_mul_f32_e64 v55, v55, v138
	v_pk_mul_f32 v[52:53], v[52:53], v[138:139] op_sel_hi:[1,0]
	v_pk_mul_f32 v[42:43], v[42:43], v[138:139] op_sel_hi:[1,0]
	s_waitcnt lgkmcnt(0)
	v_mfma_f32_16x16x32_bf16 v[48:51], v[178:181], v[44:47], v[48:51]
	v_mul_f32_e64 v40, v40, v138
	v_mul_f32_e64 v41, v41, v138
	v_pk_mul_f32 v[34:35], v[34:35], v[138:139] op_sel_hi:[1,0]
	v_pk_mul_f32 v[32:33], v[32:33], v[138:139] op_sel_hi:[1,0]
	v_mfma_f32_16x16x32_bf16 v[36:39], v[186:189], v[68:71], v[36:39]
	s_waitcnt vmcnt(12)
	v_lshlrev_b32_e32 v70, 16, v84
	v_and_b32_e32 v71, 0xffff0000, v84
	v_pk_add_f32 v[48:49], v[70:71], v[48:49] neg_lo:[0,1] neg_hi:[0,1]
	v_lshlrev_b32_e32 v70, 16, v85
	v_and_b32_e32 v71, 0xffff0000, v85
	v_pk_add_f32 v[50:51], v[70:71], v[50:51] neg_lo:[0,1] neg_hi:[0,1]
	v_cvt_pk_bf16_f32 v48, v48, v49
	v_cvt_pk_bf16_f32 v49, v50, v51
	v_add_u32_e32 v50, v155, v158
	ds_write_b64 v50, v[48:49] offset:34816
	ds_read_b128 v[48:51], v164
	v_lshl_add_u64 v[68:69], v[80:81], 0, s[0:1]
	ds_read_b128 v[80:83], v164 offset:64
	v_lshl_add_u64 v[68:69], v[68:69], 0, v[122:123]
	s_waitcnt lgkmcnt(1)
	v_mfma_f32_16x16x32_bf16 v[88:91], v[88:91], v[48:51], 0
	v_add_u32_e32 v84, s50, v154
	v_pk_mul_f32 v[26:27], v[26:27], v[138:139] op_sel_hi:[1,0]
	v_pk_mul_f32 v[24:25], v[24:25], v[138:139] op_sel_hi:[1,0]
	v_mfma_f32_16x16x32_bf16 v[214:217], v[190:193], v[44:47], v[36:39]
	v_mul_f32_e64 v78, v78, v138
	v_mul_f32_e64 v79, v79, v138
	v_pk_mul_f32 v[76:77], v[76:77], v[138:139] op_sel_hi:[1,0]
	v_lshl_add_u64 v[36:37], v[68:69], 0, v[114:115]
	v_lshl_add_u64 v[38:39], v[36:37], 0, s[24:25]
	v_add_co_u32_e32 v36, vcc, s38, v36
	global_load_dwordx4 v[68:71], v[218:219], off
	global_load_dwordx4 v[44:47], v[218:219], off offset:64
	v_addc_co_u32_e32 v37, vcc, 0, v37, vcc
	v_mfma_f32_16x16x32_bf16 v[100:103], v[100:103], v[48:51], 0
	global_load_dwordx4 v[48:51], v[36:37], off
	s_nop 0
	global_load_dwordx4 v[36:39], v[38:39], off offset:64
	s_nop 0
	global_load_dword v123, v115, s[30:31]
	s_waitcnt lgkmcnt(0)
	v_mfma_f32_16x16x32_bf16 v[88:91], v[104:107], v[80:83], v[88:91]
	ds_read_b128 v[104:107], v164 offset:128
	v_mad_i64_i32 v[84:85], s[30:31], v84, s40, v[202:203]
	v_mfma_f32_16x16x32_bf16 v[80:83], v[182:185], v[80:83], v[100:103]
	v_lshl_add_u64 v[84:85], v[84:85], 0, s[0:1]
	s_nop 1
	ds_read_b128 v[100:103], v164 offset:192
	s_waitcnt lgkmcnt(1)
	v_mfma_f32_16x16x32_bf16 v[88:91], v[108:111], v[104:107], v[88:91]
	v_mfma_f32_16x16x32_bf16 v[104:107], v[186:189], v[104:107], v[80:83]
	s_nop 2
	v_lshl_add_u64 v[80:81], v[84:85], 0, v[126:127]
	s_waitcnt lgkmcnt(0)
	v_mfma_f32_16x16x32_bf16 v[108:111], v[178:181], v[100:103], v[88:91]
	v_lshl_add_u64 v[84:85], v[80:81], 0, s[26:27]
	v_add_co_u32_e32 v80, vcc, s38, v80
	v_mfma_f32_16x16x32_bf16 v[178:181], v[190:193], v[100:103], v[104:107]
	s_nop 0
	v_addc_co_u32_e32 v81, vcc, 0, v81, vcc
	global_load_dwordx4 v[80:83], v[80:81], off offset:2048
	s_nop 0
	global_load_dwordx4 v[88:91], v[84:85], off offset:16
	v_lshlrev_b32_e32 v84, 16, v86
	v_and_b32_e32 v85, 0xffff0000, v86
	v_lshlrev_b32_e32 v86, 16, v87
	v_and_b32_e32 v87, 0xffff0000, v87
	v_pk_add_f32 v[84:85], v[84:85], v[108:109] neg_lo:[0,1] neg_hi:[0,1]
	v_pk_add_f32 v[86:87], v[86:87], v[110:111] neg_lo:[0,1] neg_hi:[0,1]
	v_cvt_pk_bf16_f32 v84, v84, v85
	v_cvt_pk_bf16_f32 v85, v86, v87
	v_add_u32_e32 v86, v155, v159
	ds_write_b64 v86, v[84:85] offset:34816
	s_waitcnt lgkmcnt(0)
	s_barrier
	ds_read_b128 v[182:185], v148 offset:34816
	ds_read_b128 v[186:189], v148 offset:34880
	ds_read_b128 v[190:193], v148 offset:37120
	ds_read_b128 v[232:235], v148 offset:37184
	s_waitcnt lgkmcnt(2)
	v_mfma_f32_16x16x32_bf16 v[64:67], v[96:99], v[182:185], v[64:67]
	v_mfma_f32_16x16x32_bf16 v[64:67], v[92:95], v[186:189], v[64:67]
	s_cmp_lg_u32 s59, 0
	s_cbranch_scc1 .Lcb_skip0
	v_mfma_f32_16x16x32_bf16 v[84:87], v[194:197], v[182:185], v[198:201]
	v_mfma_f32_16x16x32_bf16 v[84:87], v[206:209], v[186:189], v[84:87]
